# hgrn pass-2 chunk: first MFMA chain fetches its 16 LDS fragments ahead into free registers (counted lgkmcnt) instead of 8 serialized read-wait-MFMA steps
# baseline (speedup 1.0000x reference)
.LBB0_292:
	s_or_b64 exec, exec, s[20:21]
	v_add_f32_e32 v229, v229, v213
	v_add_f32_e32 v239, v239, v213
	v_mul_f32_e32 v222, 0xbfb8aa3b, v229
	v_mul_f32_e32 v223, 0xbfb8aa3b, v239
	v_exp_f32_e32 v222, v222
	v_exp_f32_e32 v223, v223
	v_ashrrev_i32_e32 v212, 3, v238
	v_pk_mul_f32 v[146:147], v[14:15], v[146:147]
	v_and_b32_e32 v224, -16, v212
	s_movk_i32 s1, 0x88
	v_mul_lo_u32 v230, v224, s1
	v_pk_mul_f32 v[144:145], v[146:147], v[144:145]
	v_lshlrev_b32_e32 v225, 1, v0
	v_or_b32_e32 v230, v230, v0
	v_pk_mul_f32 v[144:145], v[144:145], v[222:223]
	v_lshl_or_b32 v215, v224, 8, v225
	v_lshlrev_b32_e32 v230, 1, v230
	v_cvt_pk_bf16_f32 v146, v144, s0
	ds_read_u16 v214, v215 offset:55808
	ds_write_b16 v230, v146 offset:8704
	ds_read_u16 v146, v215 offset:47616
	v_mul_f32_e32 v222, 0x3fb8aa3b, v229
	v_exp_f32_e32 v222, v222
	v_add_f32_e32 v240, v240, v213
	v_cvt_pk_bf16_f32 v144, v144, v145
	s_waitcnt lgkmcnt(0)
	v_lshlrev_b32_e32 v146, 16, v146
	v_mul_f32_e32 v147, 0xbfb8aa3b, v146
	v_exp_f32_e32 v147, v147
	s_movk_i32 s70, 0x88
	v_add_f32_e32 v147, 1.0, v147
	v_rcp_f32_e32 v147, v147
	s_nop 0
	v_mul_f32_e32 v146, v147, v146
	v_mul_f32_e32 v146, v222, v146
	v_cvt_pk_bf16_f32 v146, v146, s0
	ds_write_b16 v230, v146
	v_cvt_pk_bf16_f32 v146, v145, s0
	ds_read_u16 v222, v215 offset:56064
	ds_write_b16 v230, v146 offset:8976
	ds_read_u16 v146, v215 offset:47872
	s_waitcnt lgkmcnt(0)
	v_lshlrev_b32_e32 v223, 16, v146
	v_mul_f32_e32 v146, 0xbfb8aa3b, v223
	v_exp_f32_e32 v229, v146
	v_pk_mul_f32 v[146:147], v[14:15], v[150:151]
	v_mul_f32_e32 v150, 0x3fb8aa3b, v239
	v_pk_mul_f32 v[146:147], v[146:147], v[148:149]
	v_add_f32_e32 v151, 1.0, v229
	v_rcp_f32_e32 v151, v151
	v_exp_f32_e32 v229, v150
	v_mul_f32_e32 v150, 0xbfb8aa3b, v240
	v_exp_f32_e32 v150, v150
	v_mul_f32_e32 v151, v151, v223
	v_mul_f32_e32 v151, v229, v151
	v_add_f32_e32 v229, v241, v213
	v_cvt_pk_bf16_f32 v223, v151, s0
	v_mul_f32_e32 v151, 0xbfb8aa3b, v229
	v_exp_f32_e32 v151, v151
	ds_write_b16 v230, v223 offset:272
	ds_read_u16 v223, v215 offset:56320
	v_pk_mul_f32 v[146:147], v[146:147], v[150:151]
	s_nop 0
	v_cvt_pk_bf16_f32 v148, v146, s0
	ds_write_b16 v230, v148 offset:9248
	ds_read_u16 v148, v215 offset:48128
	v_mul_f32_e32 v150, 0x3fb8aa3b, v240
	v_exp_f32_e32 v150, v150
	v_cvt_pk_bf16_f32 v151, v147, s0
	s_waitcnt lgkmcnt(0)
	v_lshlrev_b32_e32 v148, 16, v148
	v_mul_f32_e32 v149, 0xbfb8aa3b, v148
	v_exp_f32_e32 v149, v149
	s_nop 0
	v_add_f32_e32 v149, 1.0, v149
	v_rcp_f32_e32 v149, v149
	s_nop 0
	v_mul_f32_e32 v148, v149, v148
	v_mul_f32_e32 v148, v150, v148
	v_cvt_pk_bf16_f32 v148, v148, s0
	ds_write_b16 v230, v148 offset:544
	ds_read_u16 v239, v215 offset:56576
	ds_write_b16 v230, v151 offset:9520
	ds_read_u16 v150, v215 offset:48384
	v_pk_mul_f32 v[148:149], v[14:15], v[154:155]
	v_add_f32_e32 v154, v242, v213
	v_add_f32_e32 v155, v243, v213
	v_mul_f32_e32 v151, 0x3fb8aa3b, v229
	s_waitcnt lgkmcnt(0)
	v_lshlrev_b32_e32 v240, 16, v150
	v_mul_f32_e32 v150, 0xbfb8aa3b, v240
	v_exp_f32_e32 v150, v150
	v_mul_f32_e32 v229, 0xbfb8aa3b, v154
	v_mul_f32_e32 v241, 0xbfb8aa3b, v155
	v_exp_f32_e32 v243, v151
	v_add_f32_e32 v150, 1.0, v150
	v_rcp_f32_e32 v242, v150
	v_exp_f32_e32 v150, v229
	v_exp_f32_e32 v151, v241
	v_pk_mul_f32 v[148:149], v[148:149], v[152:153]
	v_mul_f32_e32 v229, v242, v240
	v_mul_f32_e32 v229, v243, v229
	v_cvt_pk_bf16_f32 v229, v229, s0
	v_pk_mul_f32 v[148:149], v[148:149], v[150:151]
	ds_write_b16 v230, v229 offset:816
	v_cvt_pk_bf16_f32 v150, v148, s0
	ds_read_u16 v229, v215 offset:56832
	ds_write_b16 v230, v150 offset:9792
	ds_read_u16 v150, v215 offset:48640
	v_mul_f32_e32 v154, 0x3fb8aa3b, v154
	v_exp_f32_e32 v154, v154
	v_mul_f32_e32 v155, 0x3fb8aa3b, v155
	v_exp_f32_e32 v155, v155
	s_waitcnt lgkmcnt(0)
	v_lshlrev_b32_e32 v152, 16, v150
	v_mul_f32_e32 v150, 0xbfb8aa3b, v152
	v_exp_f32_e32 v153, v150
	v_pk_mul_f32 v[150:151], v[14:15], v[158:159]
	v_cvt_pk_bf16_f32 v159, v149, s0
	v_add_f32_e32 v158, v244, v213
	v_add_f32_e32 v153, 1.0, v153
	v_rcp_f32_e32 v153, v153
	v_pk_mul_f32 v[150:151], v[150:151], v[156:157]
	v_mul_u32_u24_e32 v157, 40, v0
	v_mul_f32_e32 v152, v153, v152
	v_mul_f32_e32 v152, v154, v152
	v_cvt_pk_bf16_f32 v152, v152, s0
	ds_write_b16 v230, v152 offset:1088
	ds_read_u16 v154, v215 offset:57088
	ds_write_b16 v230, v159 offset:10064
	ds_read_u16 v152, v215 offset:48896
	v_add_f32_e32 v159, v245, v213
	v_mul_f32_e32 v153, 0xbfb8aa3b, v158
	v_mul_f32_e32 v240, 0xbfb8aa3b, v159
	v_mul_f32_e32 v158, 0x3fb8aa3b, v158
	s_waitcnt lgkmcnt(0)
	v_lshlrev_b32_e32 v241, 16, v152
	v_mul_f32_e32 v152, 0xbfb8aa3b, v241
	v_exp_f32_e32 v242, v152
	v_exp_f32_e32 v152, v153
	v_exp_f32_e32 v153, v240
	v_exp_f32_e32 v158, v158
	v_add_f32_e32 v156, 1.0, v242
	v_rcp_f32_e32 v156, v156
	v_pk_mul_f32 v[150:151], v[150:151], v[152:153]
	v_mul_f32_e32 v159, 0x3fb8aa3b, v159
	v_cvt_pk_bf16_f32 v152, v150, s0
	v_mul_f32_e32 v153, v156, v241
	v_mul_f32_e32 v153, v155, v153
	v_cvt_pk_bf16_f32 v153, v153, s0
	ds_write_b16 v230, v153 offset:1360
	ds_read_u16 v155, v215 offset:57344
	ds_write_b16 v230, v152 offset:10336
	ds_read_u16 v156, v215 offset:49152
	v_pk_mul_f32 v[152:153], v[14:15], v[162:163]
	v_lshlrev_b32_e32 v163, 1, v224
	v_cvt_pk_bf16_f32 v224, v151, s0
	v_exp_f32_e32 v159, v159
	s_waitcnt lgkmcnt(0)
	v_lshlrev_b32_e32 v156, 16, v156
	v_mul_f32_e32 v162, 0xbfb8aa3b, v156
	v_exp_f32_e32 v162, v162
	v_lshl_add_u32 v157, v157, 1, v163
	v_lshlrev_b32_e32 v163, 16, v222
	v_lshlrev_b32_e32 v222, 16, v239
	v_add_f32_e32 v162, 1.0, v162
	v_rcp_f32_e32 v162, v162
	v_lshlrev_b32_e32 v154, 16, v154
	v_lshlrev_b32_e32 v155, 16, v155
	v_mul_f32_e32 v156, v162, v156
	v_mul_f32_e32 v156, v158, v156
	v_cvt_pk_bf16_f32 v156, v156, s0
	ds_write_b16 v230, v156 offset:1632
	ds_read_u16 v156, v215 offset:57600
	ds_write_b16 v230, v224 offset:10608
	ds_read_u16 v158, v215 offset:49408
	v_lshlrev_b32_e32 v162, 16, v214
	v_lshlrev_b32_e32 v214, 16, v223
	v_lshlrev_b32_e32 v223, 16, v229
	s_waitcnt lgkmcnt(2)
	v_lshlrev_b32_e32 v156, 16, v156
	s_waitcnt lgkmcnt(0)
	v_lshlrev_b32_e32 v145, 16, v158
	v_mul_f32_e32 v158, 0xbfb8aa3b, v145
	v_exp_f32_e32 v158, v158
	s_nop 0
	v_add_f32_e32 v158, 1.0, v158
	v_rcp_f32_e32 v158, v158
	s_nop 0
	v_mul_f32_e32 v145, v158, v145
	v_mul_f32_e32 v145, v159, v145
	v_cvt_pk_bf16_f32 v145, v145, s0
	ds_write_b16 v230, v145 offset:1904
	v_cvt_pk_bf16_f32 v145, v146, v147
	v_cvt_pk_bf16_f32 v147, v150, v151
	v_add_f32_e32 v150, v246, v213
	v_add_f32_e32 v151, v247, v213
	v_cvt_pk_bf16_f32 v146, v148, v149
	v_mul_f32_e32 v148, 0xbfb8aa3b, v150
	v_mul_f32_e32 v149, 0xbfb8aa3b, v151
	v_exp_f32_e32 v148, v148
	v_exp_f32_e32 v149, v149
	ds_write_b128 v157, v[144:147] offset:17408
	v_cvt_pk_bf16_f32 v144, v162, v163
	v_cvt_pk_bf16_f32 v145, v214, v222
	v_cvt_pk_bf16_f32 v146, v223, v154
	v_cvt_pk_bf16_f32 v147, v155, v156
	ds_write_b128 v157, v[144:147] offset:27648
	v_pk_mul_f32 v[144:145], v[152:153], v[160:161]
	ds_read_u16 v154, v215 offset:57856
	v_pk_mul_f32 v[144:145], v[144:145], v[148:149]
	v_mul_f32_e32 v148, 0x3fb8aa3b, v150
	v_cvt_pk_bf16_f32 v146, v144, s0
	ds_write_b16 v230, v146 offset:10880
	ds_read_u16 v146, v215 offset:49664
	v_exp_f32_e32 v148, v148
	v_add_f32_e32 v152, v249, v213
	v_add_f32_e32 v153, v250, v213
	v_add_f32_e32 v159, v251, v213
	s_waitcnt lgkmcnt(0)
	v_lshlrev_b32_e32 v146, 16, v146
	v_mul_f32_e32 v147, 0xbfb8aa3b, v146
	v_exp_f32_e32 v147, v147
	v_add_f32_e32 v162, v219, v213
	v_add_f32_e32 v163, v218, v213
	v_lshlrev_b32_e32 v154, 16, v154
	v_add_f32_e32 v147, 1.0, v147
	v_rcp_f32_e32 v147, v147
	v_cvt_pk_bf16_f32 v144, v144, v145
	v_mul_f32_e32 v146, v147, v146
	v_mul_f32_e32 v146, v148, v146
	v_cvt_pk_bf16_f32 v146, v146, s0
	ds_write_b16 v230, v146 offset:2176
	v_cvt_pk_bf16_f32 v146, v145, s0
	ds_read_u16 v155, v215 offset:58112
	ds_write_b16 v230, v146 offset:11152
	ds_read_u16 v146, v215 offset:49920
	s_waitcnt lgkmcnt(2)
	v_lshlrev_b32_e32 v155, 16, v155
	s_waitcnt lgkmcnt(0)
	v_lshlrev_b32_e32 v148, 16, v146
	v_mul_f32_e32 v146, 0xbfb8aa3b, v148
	v_exp_f32_e32 v146, v146
	s_nop 0
	v_add_f32_e32 v146, 1.0, v146
	v_rcp_f32_e32 v149, v146
	v_mul_f32_e32 v146, 0x3fb8aa3b, v151
	v_exp_f32_e32 v150, v146
	v_add_f32_e32 v151, v248, v213
	v_mul_f32_e32 v148, v149, v148
	v_mul_f32_e32 v149, 0xbfb8aa3b, v152
	v_mul_f32_e32 v148, v150, v148
	v_cvt_pk_bf16_f32 v150, v148, s0
	v_mul_f32_e32 v148, 0xbfb8aa3b, v151
	v_exp_f32_e32 v148, v148
	v_exp_f32_e32 v149, v149
	v_pk_mul_f32 v[146:147], v[14:15], v[166:167]
	ds_write_b16 v230, v150 offset:2448
	v_pk_mul_f32 v[146:147], v[146:147], v[164:165]
	ds_read_u16 v156, v215 offset:58368
	v_pk_mul_f32 v[146:147], v[146:147], v[148:149]
	v_mul_f32_e32 v150, 0x3fb8aa3b, v151
	v_cvt_pk_bf16_f32 v148, v146, s0
	ds_write_b16 v230, v148 offset:11424
	ds_read_u16 v148, v215 offset:50176
	v_exp_f32_e32 v150, v150
	v_or_b32_e32 v164, 15, v212
	v_lshl_or_b32 v165, v164, 8, v225
	s_waitcnt lgkmcnt(2)
	v_lshlrev_b32_e32 v156, 16, v156
	s_waitcnt lgkmcnt(0)
	v_lshlrev_b32_e32 v148, 16, v148
	v_mul_f32_e32 v149, 0xbfb8aa3b, v148
	v_exp_f32_e32 v149, v149
	v_cvt_pk_bf16_f32 v145, v146, v147
	v_add_f32_e32 v149, 1.0, v149
	v_rcp_f32_e32 v149, v149
	s_nop 0
	v_mul_f32_e32 v148, v149, v148
	v_mul_f32_e32 v148, v150, v148
	v_cvt_pk_bf16_f32 v148, v148, s0
	ds_write_b16 v230, v148 offset:2720
	v_cvt_pk_bf16_f32 v148, v147, s0
	ds_read_u16 v158, v215 offset:58624
	ds_write_b16 v230, v148 offset:11696
	ds_read_u16 v148, v215 offset:50432
	s_waitcnt lgkmcnt(2)
	v_lshlrev_b32_e32 v158, 16, v158
	s_waitcnt lgkmcnt(0)
	v_lshlrev_b32_e32 v150, 16, v148
	v_mul_f32_e32 v148, 0xbfb8aa3b, v150
	v_exp_f32_e32 v148, v148
	s_nop 0
	v_add_f32_e32 v148, 1.0, v148
	v_rcp_f32_e32 v151, v148
	v_mul_f32_e32 v148, 0x3fb8aa3b, v152
	v_exp_f32_e32 v152, v148
	v_pk_mul_f32 v[148:149], v[14:15], v[170:171]
	v_mul_f32_e32 v150, v151, v150
	v_mul_f32_e32 v151, 0xbfb8aa3b, v159
	v_mul_f32_e32 v150, v152, v150
	v_cvt_pk_bf16_f32 v152, v150, s0
	v_mul_f32_e32 v150, 0xbfb8aa3b, v153
	v_exp_f32_e32 v150, v150
	v_exp_f32_e32 v151, v151
	v_pk_mul_f32 v[148:149], v[148:149], v[168:169]
	ds_write_b16 v230, v152 offset:2992
	ds_read_u16 v160, v215 offset:58880
	v_pk_mul_f32 v[148:149], v[148:149], v[150:151]
	v_mul_f32_e32 v152, 0x3fb8aa3b, v153
	v_cvt_pk_bf16_f32 v150, v148, s0
	ds_write_b16 v230, v150 offset:11968
	ds_read_u16 v150, v215 offset:50688
	v_exp_f32_e32 v152, v152
	s_waitcnt lgkmcnt(2)
	v_lshlrev_b32_e32 v160, 16, v160
	v_cvt_pk_bf16_f32 v146, v148, v149
	s_waitcnt lgkmcnt(0)
	v_lshlrev_b32_e32 v150, 16, v150
	v_mul_f32_e32 v151, 0xbfb8aa3b, v150
	v_exp_f32_e32 v151, v151
	s_nop 0
	v_add_f32_e32 v151, 1.0, v151
	v_rcp_f32_e32 v151, v151
	s_nop 0
	v_mul_f32_e32 v150, v151, v150
	v_mul_f32_e32 v150, v152, v150
	v_cvt_pk_bf16_f32 v150, v150, s0
	ds_write_b16 v230, v150 offset:3264
	v_cvt_pk_bf16_f32 v150, v149, s0
	ds_read_u16 v161, v215 offset:59136
	ds_write_b16 v230, v150 offset:12240
	ds_read_u16 v150, v215 offset:50944
	s_waitcnt lgkmcnt(2)
	v_lshlrev_b32_e32 v161, 16, v161
	s_waitcnt lgkmcnt(0)
	v_lshlrev_b32_e32 v152, 16, v150
	v_mul_f32_e32 v150, 0xbfb8aa3b, v152
	v_exp_f32_e32 v150, v150
	s_nop 0
	v_add_f32_e32 v150, 1.0, v150
	v_rcp_f32_e32 v153, v150
	v_mul_f32_e32 v150, 0x3fb8aa3b, v159
	v_exp_f32_e32 v159, v150
	v_pk_mul_f32 v[150:151], v[14:15], v[174:175]
	v_mul_f32_e32 v152, v153, v152
	v_mul_f32_e32 v153, 0xbfb8aa3b, v163
	v_mul_f32_e32 v152, v159, v152
	v_cvt_pk_bf16_f32 v159, v152, s0
	v_mul_f32_e32 v152, 0xbfb8aa3b, v162
	v_exp_f32_e32 v152, v152
	v_exp_f32_e32 v153, v153
	v_pk_mul_f32 v[150:151], v[150:151], v[172:173]
	ds_write_b16 v230, v159 offset:3536
	ds_read_u16 v159, v215 offset:59392
	v_pk_mul_f32 v[150:151], v[150:151], v[152:153]
	v_mul_f32_e32 v162, 0x3fb8aa3b, v162
	v_cvt_pk_bf16_f32 v152, v150, s0
	ds_write_b16 v230, v152 offset:12512
	ds_read_u16 v152, v215 offset:51200
	v_exp_f32_e32 v162, v162
	v_mul_f32_e32 v163, 0x3fb8aa3b, v163
	v_exp_f32_e32 v163, v163
	s_waitcnt lgkmcnt(2)
	v_lshlrev_b32_e32 v159, 16, v159
	s_waitcnt lgkmcnt(0)
	v_lshlrev_b32_e32 v152, 16, v152
	v_mul_f32_e32 v153, 0xbfb8aa3b, v152
	v_exp_f32_e32 v153, v153
	v_cvt_pk_bf16_f32 v147, v150, v151
	v_add_f32_e32 v153, 1.0, v153
	v_rcp_f32_e32 v153, v153
	s_nop 0
	v_mul_f32_e32 v152, v153, v152
	v_mul_f32_e32 v152, v162, v152
	v_cvt_pk_bf16_f32 v152, v152, s0
	v_mul_lo_u32 v162, v164, s1
	ds_write_b16 v230, v152 offset:3808
	v_cvt_pk_bf16_f32 v153, v151, s0
	v_add_lshl_u32 v0, v162, v0, 1
	ds_read_u16 v152, v165 offset:55808
	ds_write_b16 v0, v153 offset:8704
	ds_read_u16 v153, v165 offset:47616
	s_waitcnt lgkmcnt(2)
	v_lshlrev_b32_e32 v152, 16, v152
	s_waitcnt lgkmcnt(0)
	v_lshlrev_b32_e32 v153, 16, v153
	v_mul_f32_e32 v162, 0xbfb8aa3b, v153
	v_exp_f32_e32 v162, v162
	s_nop 0
	v_add_f32_e32 v162, 1.0, v162
	v_rcp_f32_e32 v162, v162
	s_nop 0
	v_mul_f32_e32 v153, v162, v153
	v_mul_f32_e32 v153, v163, v153
	v_cvt_pk_bf16_f32 v153, v153, s0
	ds_write_b16 v0, v153
	ds_write_b128 v157, v[144:147] offset:17424
	v_cvt_pk_bf16_f32 v144, v154, v155
	v_cvt_pk_bf16_f32 v145, v156, v158
	v_cvt_pk_bf16_f32 v146, v160, v161
	v_cvt_pk_bf16_f32 v147, v159, v152
	ds_write_b128 v157, v[144:147] offset:27664
	s_waitcnt lgkmcnt(0)
	s_barrier
	s_nop 0
	v_and_b32_e32 v0, 31, v238
	v_bfe_u32 v212, v238, 5, 1
	s_setprio 1
	v_mul_u32_u24_e32 v144, 0x88, v0
	v_lshlrev_b32_e32 v145, 4, v212
	v_lshl_add_u32 v214, v144, 1, v145
	ds_read_b128 v[16:19], v214 offset:8704
	ds_read_b128 v[20:23], v214
	ds_read_b128 v[24:27], v214 offset:32
	ds_read_b128 v[28:31], v214 offset:8736
	ds_read_b128 v[32:35], v214 offset:8768
	ds_read_b128 v[36:39], v214 offset:64
	ds_read_b128 v[40:43], v214 offset:8800
	ds_read_b128 v[44:47], v214 offset:96
	ds_read_b128 v[48:51], v214 offset:8832
	ds_read_b128 v[52:55], v214 offset:128
	ds_read_b128 v[56:59], v214 offset:8864
	ds_read_b128 v[60:63], v214 offset:160
	ds_read_b128 v[64:67], v214 offset:8896
	ds_read_b128 v[68:71], v214 offset:192
	ds_read_b128 v[72:75], v214 offset:8928
	s_waitcnt lgkmcnt(13)
	v_mfma_f32_32x32x16_bf16 v[144:159], v[16:19], v[20:23], 0
	ds_read_b128 v[76:79], v214 offset:224
	v_lshlrev_b32_e32 v215, 2, v212
	v_lshlrev_b32_e32 v213, 3, v212
	v_or_b32_e32 v212, 1, v215
	s_waitcnt lgkmcnt(12)
	v_mfma_f32_32x32x16_bf16 v[160:175], v[28:31], v[24:27], 0
	s_waitcnt lgkmcnt(10)
	v_mfma_f32_32x32x16_bf16 v[144:159], v[32:35], v[36:39], v[144:159]
	s_waitcnt lgkmcnt(8)
	v_mfma_f32_32x32x16_bf16 v[160:175], v[40:43], v[44:47], v[160:175]
	s_waitcnt lgkmcnt(6)
	v_mfma_f32_32x32x16_bf16 v[144:159], v[48:51], v[52:55], v[144:159]
	s_waitcnt lgkmcnt(4)
	v_mfma_f32_32x32x16_bf16 v[160:175], v[56:59], v[60:63], v[160:175]
	s_waitcnt lgkmcnt(2)
	v_mfma_f32_32x32x16_bf16 v[144:159], v[64:67], v[68:71], v[144:159]
	s_waitcnt lgkmcnt(0)
	v_mfma_f32_32x32x16_bf16 v[160:175], v[72:75], v[76:79], v[160:175]
	s_nop 11
	v_pk_add_f32 v[150:151], v[150:151], v[166:167]
	v_pk_add_f32 v[148:149], v[148:149], v[164:165]
	v_pk_add_f32 v[146:147], v[146:147], v[162:163]
	v_pk_add_f32 v[158:159], v[158:159], v[174:175]
	v_pk_add_f32 v[156:157], v[156:157], v[172:173]
	v_pk_add_f32 v[154:155], v[154:155], v[170:171]
	v_pk_add_f32 v[152:153], v[152:153], v[168:169]
	v_pk_add_f32 v[144:145], v[144:145], v[160:161]
	v_or_b32_e32 v163, 3, v215
	v_or_b32_e32 v164, 2, v215
	v_or_b32_e32 v165, 9, v215
	v_or_b32_e32 v166, 8, v215
	v_or_b32_e32 v167, 11, v215
	v_or_b32_e32 v168, 10, v215
	v_or_b32_e32 v160, 17, v215
	v_or_b32_e32 v161, 16, v215
	v_or_b32_e32 v162, 19, v215
	v_or_b32_e32 v169, 18, v215
	v_or_b32_e32 v170, 25, v215
	v_or_b32_e32 v171, 24, v215
	v_or_b32_e32 v172, 27, v215
	v_or_b32_e32 v173, 26, v215
	v_cvt_pk_bf16_f32 v152, v152, v153
	v_cmp_ge_u32_e32 vcc, v161, v0
	v_cvt_pk_bf16_f32 v144, v144, v145
	v_ashrrev_i32_e32 v174, 1, v238
	v_cndmask_b32_e32 v153, 0, v152, vcc
	v_lshrrev_b32_e32 v152, 16, v152
	v_cmp_ge_u32_e32 vcc, v160, v0
	s_movk_i32 s1, 0xffe0
	v_bfi_b32 v175, s1, v174, v238
	v_cndmask_b32_e32 v152, 0, v152, vcc
	v_perm_b32 v160, v152, v153, s78
	v_cvt_pk_bf16_f32 v152, v154, v155
	v_cmp_ge_u32_e32 vcc, v169, v0
	v_mul_lo_u32 v175, v175, s87
	v_or_b32_e32 v175, v175, v213
	v_cndmask_b32_e32 v153, 0, v152, vcc
	v_lshrrev_b32_e32 v152, 16, v152
	v_cmp_ge_u32_e32 vcc, v162, v0
	s_nop 1
	v_cndmask_b32_e32 v152, 0, v152, vcc
	v_perm_b32 v161, v152, v153, s78
	v_cvt_pk_bf16_f32 v152, v156, v157
	v_cmp_ge_u32_e32 vcc, v171, v0
	s_nop 1
	v_cndmask_b32_e32 v153, 0, v152, vcc
	v_lshrrev_b32_e32 v152, 16, v152
	v_cmp_ge_u32_e32 vcc, v170, v0
	s_nop 1
	v_cndmask_b32_e32 v152, 0, v152, vcc
	v_cmp_ge_u32_e32 vcc, v215, v0
	v_perm_b32 v162, v152, v153, s78
	v_cvt_pk_bf16_f32 v152, v158, v159
	v_cndmask_b32_e32 v145, 0, v144, vcc
	v_lshrrev_b32_e32 v144, 16, v144
	v_cmp_ge_u32_e32 vcc, v212, v0
	v_and_b32_e32 v212, 0xffffffe0, v174
	s_nop 0
	v_cndmask_b32_e32 v144, 0, v144, vcc
	v_perm_b32 v144, v144, v145, s78
	v_cvt_pk_bf16_f32 v145, v146, v147
	v_cmp_ge_u32_e32 vcc, v164, v0
	v_add_u32_e32 v164, 0x6800, v175
	s_nop 0
	v_cndmask_b32_e32 v146, 0, v145, vcc
	v_lshrrev_b32_e32 v145, 16, v145
	v_cmp_ge_u32_e32 vcc, v163, v0
	s_nop 1
	v_cndmask_b32_e32 v145, 0, v145, vcc
	v_perm_b32 v145, v145, v146, s78
	v_cvt_pk_bf16_f32 v146, v148, v149
	v_cmp_ge_u32_e32 vcc, v166, v0
	s_nop 1
	v_cndmask_b32_e32 v147, 0, v146, vcc
	v_lshrrev_b32_e32 v146, 16, v146
	v_cmp_ge_u32_e32 vcc, v165, v0
	v_lshrrev_b32_e32 v165, 16, v152
	s_nop 0
	v_cndmask_b32_e32 v146, 0, v146, vcc
	v_perm_b32 v146, v146, v147, s78
	v_cvt_pk_bf16_f32 v147, v150, v151
	v_cmp_ge_u32_e32 vcc, v168, v0
	s_nop 1
	v_cndmask_b32_e32 v148, 0, v147, vcc
	v_lshrrev_b32_e32 v147, 16, v147
	v_cmp_ge_u32_e32 vcc, v167, v0
	s_nop 1
	v_cndmask_b32_e32 v147, 0, v147, vcc
	v_perm_b32 v147, v147, v148, s78
	ds_read2_b64 v[148:151], v164 offset0:128 offset1:130
	v_cmp_ge_u32_e32 vcc, v173, v0
	s_nop 1
	v_cndmask_b32_e32 v163, 0, v152, vcc
	s_waitcnt lgkmcnt(0)
	v_mfma_f32_32x32x16_bf16 v[144:159], v[144:147], v[148:151], 0
	v_cmp_ge_u32_e32 vcc, v172, v0
	s_nop 1
	v_cndmask_b32_e32 v165, 0, v165, vcc
	v_perm_b32 v163, v165, v163, s78
	ds_read2_b64 v[164:167], v164 offset0:132 offset1:134
	s_waitcnt lgkmcnt(0)
	v_mfma_f32_32x32x16_bf16 v[144:159], v[160:163], v[164:167], v[144:159]
	v_sub_u32_e32 v213, v214, v213
	ds_read2_b64 v[160:163], v213 offset1:2
	v_cvt_pk_bf16_f32 v164, v128, v129
	v_cvt_pk_bf16_f32 v165, v130, v131
	v_cvt_pk_bf16_f32 v166, v132, v133
	v_cvt_pk_bf16_f32 v167, v134, v135
	ds_read2_b64 v[240:243], v213 offset0:8 offset1:10
	v_cvt_pk_bf16_f32 v244, v112, v113
	v_cvt_pk_bf16_f32 v245, v114, v115
	v_cvt_pk_bf16_f32 v246, v116, v117
	s_waitcnt lgkmcnt(1)
	v_mfma_f32_32x32x16_bf16 v[144:159], v[160:163], v[164:167], v[144:159]
	ds_read2_b64 v[160:163], v213 offset0:4 offset1:6
	v_cvt_pk_bf16_f32 v247, v118, v119
	v_cvt_pk_bf16_f32 v164, v136, v137
	v_cvt_pk_bf16_f32 v165, v138, v139
	v_cvt_pk_bf16_f32 v166, v140, v141
	v_cvt_pk_bf16_f32 v167, v142, v143
	s_waitcnt lgkmcnt(1)
	v_mfma_f32_32x32x16_bf16 v[144:159], v[240:243], v[244:247], v[144:159]
	ds_read2_b64 v[240:243], v213 offset0:12 offset1:14
	v_cvt_pk_bf16_f32 v244, v120, v121
	v_cvt_pk_bf16_f32 v245, v122, v123
	v_cvt_pk_bf16_f32 v246, v124, v125
	v_cvt_pk_bf16_f32 v247, v126, v127
	s_waitcnt lgkmcnt(1)
	v_mfma_f32_32x32x16_bf16 v[160:175], v[160:163], v[164:167], 0
	s_waitcnt lgkmcnt(0)
	v_mfma_f32_32x32x16_bf16 v[160:175], v[240:243], v[244:247], v[160:175]
	ds_read2_b64 v[240:243], v213 offset0:16 offset1:18
	v_cvt_pk_bf16_f32 v244, v96, v97
	v_cvt_pk_bf16_f32 v245, v98, v99
	v_cvt_pk_bf16_f32 v246, v100, v101
	v_cvt_pk_bf16_f32 v247, v102, v103
	s_waitcnt lgkmcnt(0)
	s_nop 0
	v_mfma_f32_32x32x16_bf16 v[144:159], v[240:243], v[244:247], v[144:159]
	ds_read2_b64 v[240:243], v213 offset0:20 offset1:22
	v_cvt_pk_bf16_f32 v244, v104, v105
	v_cvt_pk_bf16_f32 v245, v106, v107
	v_cvt_pk_bf16_f32 v246, v108, v109
	v_cvt_pk_bf16_f32 v247, v110, v111
	s_waitcnt lgkmcnt(0)
	s_nop 0
	v_mfma_f32_32x32x16_bf16 v[160:175], v[240:243], v[244:247], v[160:175]
	ds_read2_b64 v[240:243], v213 offset0:24 offset1:26
	v_cvt_pk_bf16_f32 v244, v80, v81
	v_cvt_pk_bf16_f32 v245, v82, v83
	v_cvt_pk_bf16_f32 v246, v84, v85
	v_cvt_pk_bf16_f32 v247, v86, v87
	s_waitcnt lgkmcnt(0)
	s_nop 0
	v_mfma_f32_32x32x16_bf16 v[144:159], v[240:243], v[244:247], v[144:159]
	ds_read2_b64 v[240:243], v213 offset0:28 offset1:30
	v_cvt_pk_bf16_f32 v244, v88, v89
	v_cvt_pk_bf16_f32 v245, v90, v91
	v_cvt_pk_bf16_f32 v246, v92, v93
	v_cvt_pk_bf16_f32 v247, v94, v95
	s_waitcnt lgkmcnt(0)
	s_nop 0
	v_mfma_f32_32x32x16_bf16 v[160:175], v[240:243], v[244:247], v[160:175]
	s_nop 11
	v_add_f32_e32 v160, v144, v160
	v_add_f32_e32 v161, v145, v161
	v_add_f32_e32 v162, v146, v162
	v_add_f32_e32 v163, v147, v163
	v_add_f32_e32 v148, v148, v164
	v_add_f32_e32 v149, v149, v165
	v_add_f32_e32 v150, v150, v166
	v_add_f32_e32 v151, v151, v167
	v_add_f32_e32 v152, v152, v168
	v_add_f32_e32 v153, v153, v169
	v_add_f32_e32 v154, v154, v170
	v_add_f32_e32 v155, v155, v171
	v_add_f32_e32 v156, v156, v172
	v_add_f32_e32 v157, v157, v173
	v_add_f32_e32 v158, v158, v174
	v_add_f32_e32 v159, v159, v175
	v_add_u32_e32 v164, s27, v215
	v_add_u32_e32 v144, 0xe0, v164
	v_ashrrev_i32_e32 v213, 31, v212
	v_lshl_add_u64 v[146:147], v[212:213], 1, s[36:37]
	v_lshlrev_b32_e32 v0, 1, v0
	v_ashrrev_i32_e32 v145, 31, v144
	v_lshl_add_u64 v[146:147], v[146:147], 0, v[0:1]
	v_lshlrev_b64 v[144:145], 10, v[144:145]
	v_cvt_pk_bf16_f32 v0, v160, s0
	v_lshl_add_u64 v[144:145], v[146:147], 0, v[144:145]
	global_store_short v[144:145], v0, off
	v_add_u32_e32 v144, 0xe1, v164
	v_ashrrev_i32_e32 v145, 31, v144
	v_lshlrev_b64 v[144:145], 10, v[144:145]
	v_cvt_pk_bf16_f32 v0, v161, s0
	v_lshl_add_u64 v[144:145], v[146:147], 0, v[144:145]
	global_store_short v[144:145], v0, off
	v_add_u32_e32 v144, 0xe2, v164
	v_ashrrev_i32_e32 v145, 31, v144
	v_lshlrev_b64 v[144:145], 10, v[144:145]
	v_cvt_pk_bf16_f32 v0, v162, s0
	v_lshl_add_u64 v[144:145], v[146:147], 0, v[144:145]
	global_store_short v[144:145], v0, off
	v_add_u32_e32 v144, 0xe3, v164
	v_ashrrev_i32_e32 v145, 31, v144
	v_lshlrev_b64 v[144:145], 10, v[144:145]
	v_cvt_pk_bf16_f32 v0, v163, s0
	v_lshl_add_u64 v[144:145], v[146:147], 0, v[144:145]
	global_store_short v[144:145], v0, off
	v_add_u32_e32 v144, 0xe8, v164
	v_ashrrev_i32_e32 v145, 31, v144
	v_lshlrev_b64 v[144:145], 10, v[144:145]
	v_cvt_pk_bf16_f32 v0, v148, s0
	v_lshl_add_u64 v[144:145], v[146:147], 0, v[144:145]
	global_store_short v[144:145], v0, off
	v_add_u32_e32 v144, 0xe9, v164
	v_ashrrev_i32_e32 v145, 31, v144
	v_lshlrev_b64 v[144:145], 10, v[144:145]
	v_cvt_pk_bf16_f32 v0, v149, s0
	v_lshl_add_u64 v[144:145], v[146:147], 0, v[144:145]
	global_store_short v[144:145], v0, off
	v_add_u32_e32 v144, 0xea, v164
	v_ashrrev_i32_e32 v145, 31, v144
	v_lshlrev_b64 v[144:145], 10, v[144:145]
	v_cvt_pk_bf16_f32 v0, v150, s0
	v_lshl_add_u64 v[144:145], v[146:147], 0, v[144:145]
	global_store_short v[144:145], v0, off
	v_add_u32_e32 v144, 0xeb, v164
	v_ashrrev_i32_e32 v145, 31, v144
	v_lshlrev_b64 v[144:145], 10, v[144:145]
	v_cvt_pk_bf16_f32 v0, v151, s0
	v_lshl_add_u64 v[144:145], v[146:147], 0, v[144:145]
	global_store_short v[144:145], v0, off
	v_add_u32_e32 v144, 0xf0, v164
	v_ashrrev_i32_e32 v145, 31, v144
	v_lshlrev_b64 v[144:145], 10, v[144:145]
	v_cvt_pk_bf16_f32 v0, v152, s0
	v_lshl_add_u64 v[144:145], v[146:147], 0, v[144:145]
	global_store_short v[144:145], v0, off
	v_add_u32_e32 v144, 0xf1, v164
	v_ashrrev_i32_e32 v145, 31, v144
	v_lshlrev_b64 v[144:145], 10, v[144:145]
	v_cvt_pk_bf16_f32 v0, v153, s0
	v_lshl_add_u64 v[144:145], v[146:147], 0, v[144:145]
	global_store_short v[144:145], v0, off
	v_add_u32_e32 v144, 0xf2, v164
	v_ashrrev_i32_e32 v145, 31, v144
	v_lshlrev_b64 v[144:145], 10, v[144:145]
	v_cvt_pk_bf16_f32 v0, v154, s0
	v_lshl_add_u64 v[144:145], v[146:147], 0, v[144:145]
	global_store_short v[144:145], v0, off
	v_add_u32_e32 v144, 0xf3, v164
	v_ashrrev_i32_e32 v145, 31, v144
	v_lshlrev_b64 v[144:145], 10, v[144:145]
	v_cvt_pk_bf16_f32 v0, v155, s0
	v_lshl_add_u64 v[144:145], v[146:147], 0, v[144:145]
	global_store_short v[144:145], v0, off
	v_add_u32_e32 v144, 0xf8, v164
	v_ashrrev_i32_e32 v145, 31, v144
	v_lshlrev_b64 v[144:145], 10, v[144:145]
	v_cvt_pk_bf16_f32 v0, v156, s0
	v_lshl_add_u64 v[144:145], v[146:147], 0, v[144:145]
	global_store_short v[144:145], v0, off
	v_add_u32_e32 v144, 0xf9, v164
	v_ashrrev_i32_e32 v145, 31, v144
	v_lshlrev_b64 v[144:145], 10, v[144:145]
	v_cvt_pk_bf16_f32 v0, v157, s0
	v_lshl_add_u64 v[144:145], v[146:147], 0, v[144:145]
	global_store_short v[144:145], v0, off
	v_add_u32_e32 v144, 0xfa, v164
	v_ashrrev_i32_e32 v145, 31, v144
	v_lshlrev_b64 v[144:145], 10, v[144:145]
	v_cvt_pk_bf16_f32 v0, v158, s0
	v_lshl_add_u64 v[144:145], v[146:147], 0, v[144:145]
	global_store_short v[144:145], v0, off
	v_add_u32_e32 v144, 0xfb, v164
	v_ashrrev_i32_e32 v145, 31, v144
	v_lshlrev_b64 v[144:145], 10, v[144:145]
	v_cvt_pk_bf16_f32 v0, v159, s0
	v_lshl_add_u64 v[144:145], v[146:147], 0, v[144:145]
	global_store_short v[144:145], v0, off
	s_setprio 1
	s_mov_b32 s1, 0xfffffe0
	v_and_b32_e32 v146, 31, v238
	v_lshrrev_b32_e32 v144, 1, v238
	v_and_b32_e32 v0, 16, v144
	v_and_or_b32 v144, v144, s1, v146
	v_mad_u64_u32 v[144:145], s[20:21], v144, s87, v[0:1]
	v_mad_u32_u24 v168, v146, s87, v0
	ds_read_b128 v[152:155], v168 offset:17408
	ds_read_b128 v[156:159], v168 offset:17440
	ds_read_b128 v[148:151], v144 offset:27648
	ds_read_b128 v[144:147], v144 offset:27680
	s_waitcnt lgkmcnt(1)
	v_mfma_f32_32x32x16_bf16 v[128:143], v[152:155], v[148:151], v[128:143]
	s_waitcnt lgkmcnt(0)
	v_mfma_f32_32x32x16_bf16 v[128:143], v[156:159], v[144:147], v[128:143]
	ds_read_b128 v[152:155], v0 offset:37888
	ds_read_b128 v[156:159], v0 offset:37920
	ds_read_b128 v[160:163], v0 offset:37952
	ds_read_b128 v[164:167], v0 offset:37984
	s_waitcnt lgkmcnt(3)
	s_nop 6
	v_pk_mul_f32 v[130:131], v[130:131], v[154:155]
	v_pk_mul_f32 v[128:129], v[128:129], v[152:153]
	ds_read_b128 v[152:155], v168 offset:19968
	s_waitcnt lgkmcnt(0)
	v_mfma_f32_32x32x16_bf16 v[112:127], v[152:155], v[148:151], v[112:127]
	ds_read_b128 v[152:155], v168 offset:20000
	v_mul_f32_e64 v142, v142, v166
	v_mul_f32_e64 v143, v143, v167
	v_mul_f32_e64 v140, v140, v164
	v_mul_f32_e64 v141, v141, v165
	v_pk_mul_f32 v[138:139], v[138:139], v[162:163]
	v_pk_mul_f32 v[136:137], v[136:137], v[160:161]
	v_pk_mul_f32 v[134:135], v[134:135], v[158:159]
	v_pk_mul_f32 v[132:133], v[132:133], v[156:157]
	s_waitcnt lgkmcnt(0)
	v_mfma_f32_32x32x16_bf16 v[112:127], v[152:155], v[144:147], v[112:127]
	ds_read_b128 v[152:155], v0 offset:38016
	ds_read_b128 v[156:159], v0 offset:38048
	ds_read_b128 v[160:163], v0 offset:38080
	ds_read_b128 v[164:167], v0 offset:38112
	s_waitcnt lgkmcnt(3)
	s_nop 6
	v_pk_mul_f32 v[114:115], v[114:115], v[154:155]
	v_pk_mul_f32 v[112:113], v[112:113], v[152:153]
	ds_read_b128 v[152:155], v168 offset:22528
	s_waitcnt lgkmcnt(0)
	v_mfma_f32_32x32x16_bf16 v[96:111], v[152:155], v[148:151], v[96:111]
	ds_read_b128 v[152:155], v168 offset:22560
	v_mul_f32_e64 v126, v126, v166
	v_mul_f32_e64 v127, v127, v167
	v_mul_f32_e64 v124, v124, v164
	v_mul_f32_e64 v125, v125, v165
	v_pk_mul_f32 v[122:123], v[122:123], v[162:163]
	v_pk_mul_f32 v[120:121], v[120:121], v[160:161]
	v_pk_mul_f32 v[118:119], v[118:119], v[158:159]
	v_pk_mul_f32 v[116:117], v[116:117], v[156:157]
	s_waitcnt lgkmcnt(0)
	v_mfma_f32_32x32x16_bf16 v[96:111], v[152:155], v[144:147], v[96:111]
	ds_read_b128 v[152:155], v0 offset:38144
	ds_read_b128 v[156:159], v0 offset:38176
	ds_read_b128 v[160:163], v0 offset:38208
	ds_read_b128 v[164:167], v0 offset:38240
	s_waitcnt lgkmcnt(3)
	s_nop 6
	v_pk_mul_f32 v[98:99], v[98:99], v[154:155]
	v_pk_mul_f32 v[96:97], v[96:97], v[152:153]
	ds_read_b128 v[152:155], v168 offset:25088
	s_waitcnt lgkmcnt(0)
	v_mfma_f32_32x32x16_bf16 v[80:95], v[152:155], v[148:151], v[80:95]
	ds_read_b128 v[148:151], v168 offset:25120
	v_mul_f32_e64 v102, v102, v158
	v_mul_f32_e64 v103, v103, v159
	v_mul_f32_e64 v100, v100, v156
	v_mul_f32_e64 v101, v101, v157
	v_pk_mul_f32 v[110:111], v[110:111], v[166:167]
	v_pk_mul_f32 v[108:109], v[108:109], v[164:165]
	v_pk_mul_f32 v[106:107], v[106:107], v[162:163]
	v_pk_mul_f32 v[104:105], v[104:105], v[160:161]
	s_waitcnt lgkmcnt(0)
	v_mfma_f32_32x32x16_bf16 v[80:95], v[148:151], v[144:147], v[80:95]
	ds_read_b128 v[144:147], v0 offset:38272
	ds_read_b128 v[148:151], v0 offset:38304
	ds_read_b128 v[152:155], v0 offset:38336
	ds_read_b128 v[156:159], v0 offset:38368
	s_waitcnt lgkmcnt(0)
	s_nop 6
	v_pk_mul_f32 v[94:95], v[94:95], v[158:159]
	v_pk_mul_f32 v[92:93], v[92:93], v[156:157]
	v_pk_mul_f32 v[90:91], v[90:91], v[154:155]
	v_pk_mul_f32 v[88:89], v[88:89], v[152:153]
	v_pk_mul_f32 v[86:87], v[86:87], v[150:151]
	v_pk_mul_f32 v[84:85], v[84:85], v[148:149]
	v_pk_mul_f32 v[82:83], v[82:83], v[146:147]
	v_pk_mul_f32 v[80:81], v[80:81], v[144:145]
	s_setprio 0
	s_sub_i32 s26, s26, 32
	s_cmpk_lg_i32 s26, 0xff00
	s_cbranch_scc0 .LBB0_297

.LBB0_300:
	s_or_b64 exec, exec, s[20:21]
	s_waitcnt lgkmcnt(0)
	v_add_f32_e32 v119, v125, v100
	v_mul_f32_e32 v118, 0xbfb8aa3b, v119
	v_mul_f32_e32 v119, 0x3fb8aa3b, v119
	v_add_f32_e32 v124, v124, v100
	v_ashrrev_i32_e32 v104, 3, v112
	v_exp_f32_e32 v125, v119
	v_mul_f32_e32 v119, 0xbfb8aa3b, v124
	v_pk_mul_f32 v[114:115], v[14:15], v[10:11]
	v_and_b32_e32 v11, -16, v104
	v_exp_f32_e32 v118, v118
	v_exp_f32_e32 v119, v119
	v_mul_u32_u24_e32 v10, 0x4c, v0
	v_lshlrev_b32_e32 v107, 1, v11
	v_add3_u32 v10, v103, v10, v107
	v_lshlrev_b32_e32 v107, 1, v0
	s_movk_i32 s1, 0x88
	v_lshl_or_b32 v103, v11, 8, v107
	v_mul_lo_u32 v11, v11, s1
	v_pk_mul_f32 v[4:5], v[114:115], v[4:5]
	v_or_b32_e32 v11, v11, v0
	v_pk_mul_f32 v[4:5], v[4:5], v[118:119]
	v_lshlrev_b32_e32 v11, 1, v11
	v_cvt_pk_bf16_f32 v114, v4, s0
	ds_read_u16 v113, v103 offset:55808
	ds_write_b16 v11, v114 offset:8704
	ds_read_u16 v114, v103 offset:47616
	v_add_f32_e32 v119, v123, v100
	v_add_f32_e32 v122, v122, v100
	v_pk_mul_f32 v[82:83], v[14:15], v[82:83]
	v_add_f32_e32 v120, v120, v100
	s_waitcnt lgkmcnt(0)
	v_lshlrev_b32_e32 v114, 16, v114
	v_mul_f32_e32 v115, 0xbfb8aa3b, v114
	v_exp_f32_e32 v115, v115
	v_pk_mul_f32 v[8:9], v[82:83], v[8:9]
	v_pk_mul_f32 v[88:89], v[14:15], v[88:89]
	v_add_f32_e32 v116, v116, v100
	v_add_f32_e32 v115, 1.0, v115
	v_rcp_f32_e32 v115, v115
	v_pk_mul_f32 v[6:7], v[88:89], v[6:7]
	v_pk_mul_f32 v[90:91], v[14:15], v[90:91]
	v_lshlrev_b32_e32 v113, 16, v113
	v_mul_f32_e32 v114, v115, v114
	v_mul_f32_e32 v114, v125, v114
	v_cvt_pk_bf16_f32 v114, v114, s0
	ds_write_b16 v11, v114
	v_cvt_pk_bf16_f32 v115, v5, s0
	ds_read_u16 v114, v103 offset:56064
	ds_write_b16 v11, v115 offset:8976
	ds_read_u16 v115, v103 offset:47872
	v_pk_mul_f32 v[2:3], v[90:91], v[2:3]
	v_cvt_pk_bf16_f32 v4, v4, v5
	s_waitcnt lgkmcnt(2)
	v_lshlrev_b32_e32 v114, 16, v114
	v_pk_mul_f32 v[96:97], v[14:15], v[96:97]
	s_waitcnt lgkmcnt(0)
	v_lshlrev_b32_e32 v115, 16, v115
	v_mul_f32_e32 v118, 0xbfb8aa3b, v115
	v_exp_f32_e32 v118, v118
	v_pk_mul_f32 v[98:99], v[14:15], v[98:99]
	v_pk_mul_f32 v[94:95], v[14:15], v[94:95]
	v_pk_mul_f32 v[92:93], v[14:15], v[92:93]
	v_add_f32_e32 v118, 1.0, v118
	v_rcp_f32_e32 v118, v118
	s_movk_i32 s70, 0x88
	v_mul_f32_e32 v115, v118, v115
	v_mul_f32_e32 v118, 0x3fb8aa3b, v124
	v_exp_f32_e32 v118, v118
	s_nop 0
	v_mul_f32_e32 v115, v118, v115
	v_mul_f32_e32 v118, 0xbfb8aa3b, v119
	v_mul_f32_e32 v119, 0x3fb8aa3b, v119
	v_exp_f32_e32 v123, v119
	v_mul_f32_e32 v119, 0xbfb8aa3b, v122
	v_exp_f32_e32 v118, v118
	v_exp_f32_e32 v119, v119
	v_cvt_pk_bf16_f32 v115, v115, s0
	ds_write_b16 v11, v115 offset:272
	ds_read_u16 v115, v103 offset:56320
	v_pk_mul_f32 v[8:9], v[8:9], v[118:119]
	v_add_f32_e32 v119, v121, v100
	v_cvt_pk_bf16_f32 v82, v8, s0
	ds_write_b16 v11, v82 offset:9248
	ds_read_u16 v82, v103 offset:48128
	s_waitcnt lgkmcnt(2)
	v_lshlrev_b32_e32 v115, 16, v115
	v_cvt_pk_bf16_f32 v5, v8, v9
	s_waitcnt lgkmcnt(0)
	v_lshlrev_b32_e32 v82, 16, v82
	v_mul_f32_e32 v83, 0xbfb8aa3b, v82
	v_exp_f32_e32 v83, v83
	s_nop 0
	v_add_f32_e32 v83, 1.0, v83
	v_rcp_f32_e32 v83, v83
	s_nop 0
	v_mul_f32_e32 v82, v83, v82
	v_mul_f32_e32 v82, v123, v82
	v_cvt_pk_bf16_f32 v82, v82, s0
	ds_write_b16 v11, v82 offset:544
	v_cvt_pk_bf16_f32 v83, v9, s0
	ds_read_u16 v82, v103 offset:56576
	ds_write_b16 v11, v83 offset:9520
	ds_read_u16 v83, v103 offset:48384
	v_add_f32_e32 v9, v108, v100
	s_waitcnt lgkmcnt(2)
	v_lshlrev_b32_e32 v82, 16, v82
	s_waitcnt lgkmcnt(0)
	v_lshlrev_b32_e32 v83, 16, v83
	v_mul_f32_e32 v118, 0xbfb8aa3b, v83
	v_exp_f32_e32 v118, v118
	s_nop 0
	v_add_f32_e32 v118, 1.0, v118
	v_rcp_f32_e32 v118, v118
	s_nop 0
	v_mul_f32_e32 v83, v118, v83
	v_mul_f32_e32 v118, 0x3fb8aa3b, v122
	v_exp_f32_e32 v118, v118
	s_nop 0
	v_mul_f32_e32 v83, v118, v83
	v_mul_f32_e32 v118, 0xbfb8aa3b, v119
	v_mul_f32_e32 v119, 0x3fb8aa3b, v119
	v_exp_f32_e32 v121, v119
	v_mul_f32_e32 v119, 0xbfb8aa3b, v120
	v_exp_f32_e32 v118, v118
	v_exp_f32_e32 v119, v119
	v_cvt_pk_bf16_f32 v83, v83, s0
	ds_write_b16 v11, v83 offset:816
	ds_read_u16 v83, v103 offset:56832
	v_pk_mul_f32 v[6:7], v[6:7], v[118:119]
	s_waitcnt lgkmcnt(0)
	v_lshlrev_b32_e32 v83, 16, v83
	v_cvt_pk_bf16_f32 v88, v6, s0
	ds_write_b16 v11, v88 offset:9792
	ds_read_u16 v88, v103 offset:48640
	v_cvt_pk_bf16_f32 v6, v6, v7
	s_waitcnt lgkmcnt(0)
	v_lshlrev_b32_e32 v88, 16, v88
	v_mul_f32_e32 v89, 0xbfb8aa3b, v88
	v_exp_f32_e32 v89, v89
	s_nop 0
	v_add_f32_e32 v89, 1.0, v89
	v_rcp_f32_e32 v89, v89
	s_nop 0
	v_mul_f32_e32 v88, v89, v88
	v_mul_f32_e32 v88, v121, v88
	v_cvt_pk_bf16_f32 v88, v88, s0
	ds_write_b16 v11, v88 offset:1088
	ds_read_u16 v88, v103 offset:57088
	s_waitcnt lgkmcnt(0)
	v_lshlrev_b32_e32 v118, 16, v88
	v_cvt_pk_bf16_f32 v88, v7, s0
	ds_write_b16 v11, v88 offset:10064
	ds_read_u16 v88, v103 offset:48896
	s_waitcnt lgkmcnt(0)
	v_lshlrev_b32_e32 v88, 16, v88
	v_mul_f32_e32 v89, 0xbfb8aa3b, v88
	v_exp_f32_e32 v89, v89
	s_nop 0
	v_add_f32_e32 v89, 1.0, v89
	v_rcp_f32_e32 v89, v89
	s_nop 0
	v_mul_f32_e32 v88, v89, v88
	v_mul_f32_e32 v89, 0x3fb8aa3b, v120
	v_exp_f32_e32 v89, v89
	s_nop 0
	v_mul_f32_e32 v88, v89, v88
	v_cvt_pk_bf16_f32 v88, v88, s0
	ds_write_b16 v11, v88 offset:1360
	ds_read_u16 v88, v103 offset:57344
	v_add_f32_e32 v89, v117, v100
	s_waitcnt lgkmcnt(0)
	v_lshlrev_b32_e32 v119, 16, v88
	v_mul_f32_e32 v88, 0xbfb8aa3b, v89
	v_mul_f32_e32 v89, 0x3fb8aa3b, v89
	v_exp_f32_e32 v117, v89
	v_mul_f32_e32 v89, 0xbfb8aa3b, v116
	v_exp_f32_e32 v88, v88
	v_exp_f32_e32 v89, v89
	s_nop 0
	v_pk_mul_f32 v[2:3], v[2:3], v[88:89]
	s_nop 0
	v_cvt_pk_bf16_f32 v88, v2, s0
	ds_write_b16 v11, v88 offset:10336
	ds_read_u16 v88, v103 offset:49152
	v_cvt_pk_bf16_f32 v7, v2, v3
	v_cvt_pk_bf16_f32 v2, v113, v114
	s_waitcnt lgkmcnt(0)
	v_lshlrev_b32_e32 v88, 16, v88
	v_mul_f32_e32 v89, 0xbfb8aa3b, v88
	v_exp_f32_e32 v89, v89
	s_nop 0
	v_add_f32_e32 v89, 1.0, v89
	v_rcp_f32_e32 v89, v89
	s_nop 0
	v_mul_f32_e32 v88, v89, v88
	v_mul_f32_e32 v88, v117, v88
	v_cvt_pk_bf16_f32 v88, v88, s0
	ds_write_b16 v11, v88 offset:1632
	v_cvt_pk_bf16_f32 v89, v3, s0
	ds_read_u16 v88, v103 offset:57600
	ds_write_b16 v11, v89 offset:10608
	ds_read_u16 v89, v103 offset:49408
	v_cvt_pk_bf16_f32 v3, v115, v82
	s_waitcnt lgkmcnt(2)
	v_lshlrev_b32_e32 v88, 16, v88
	s_waitcnt lgkmcnt(0)
	v_lshlrev_b32_e32 v89, 16, v89
	v_mul_f32_e32 v90, 0xbfb8aa3b, v89
	v_exp_f32_e32 v90, v90
	s_nop 0
	v_add_f32_e32 v90, 1.0, v90
	v_rcp_f32_e32 v90, v90
	s_nop 0
	v_mul_f32_e32 v89, v90, v89
	v_mul_f32_e32 v90, 0x3fb8aa3b, v116
	v_exp_f32_e32 v90, v90
	s_nop 0
	v_mul_f32_e32 v89, v90, v89
	v_cvt_pk_bf16_f32 v89, v89, s0
	ds_write_b16 v11, v89 offset:1904
	ds_write_b128 v10, v[4:7] offset:17408
	v_cvt_pk_bf16_f32 v4, v83, v118
	v_cvt_pk_bf16_f32 v5, v119, v88
	ds_write_b128 v10, v[2:5] offset:27648
	ds_read_u16 v2, v103 offset:57856
	v_add_f32_e32 v3, v111, v100
	v_add_f32_e32 v7, v110, v100
	v_pk_mul_f32 v[4:5], v[96:97], v[12:13]
	v_add_f32_e32 v13, v105, v100
	s_waitcnt lgkmcnt(0)
	v_lshlrev_b32_e32 v82, 16, v2
	v_mul_f32_e32 v2, 0xbfb8aa3b, v3
	v_mul_f32_e32 v3, 0x3fb8aa3b, v3
	v_exp_f32_e32 v6, v3
	v_mul_f32_e32 v3, 0xbfb8aa3b, v7
	v_exp_f32_e32 v2, v2
	v_exp_f32_e32 v3, v3
	v_or_b32_e32 v90, 15, v104
	v_lshl_or_b32 v91, v90, 8, v107
	v_pk_mul_f32 v[2:3], v[4:5], v[2:3]
	s_nop 0
	v_cvt_pk_bf16_f32 v4, v2, s0
	ds_write_b16 v11, v4 offset:10880
	ds_read_u16 v4, v103 offset:49664
	v_cvt_pk_bf16_f32 v2, v2, v3
	s_waitcnt lgkmcnt(0)
	v_lshlrev_b32_e32 v4, 16, v4
	v_mul_f32_e32 v5, 0xbfb8aa3b, v4
	v_exp_f32_e32 v5, v5
	s_nop 0
	v_add_f32_e32 v5, 1.0, v5
	v_rcp_f32_e32 v5, v5
	s_nop 0
	v_mul_f32_e32 v4, v5, v4
	v_mul_f32_e32 v4, v6, v4
	v_cvt_pk_bf16_f32 v4, v4, s0
	ds_write_b16 v11, v4 offset:2176
	ds_read_u16 v4, v103 offset:58112
	s_waitcnt lgkmcnt(0)
	v_lshlrev_b32_e32 v83, 16, v4
	v_cvt_pk_bf16_f32 v4, v3, s0
	ds_write_b16 v11, v4 offset:11152
	ds_read_u16 v4, v103 offset:49920
	s_waitcnt lgkmcnt(0)
	v_lshlrev_b32_e32 v4, 16, v4
	v_mul_f32_e32 v5, 0xbfb8aa3b, v4
	v_exp_f32_e32 v5, v5
	s_nop 0
	v_add_f32_e32 v5, 1.0, v5
	v_rcp_f32_e32 v5, v5
	s_nop 0
	v_mul_f32_e32 v4, v5, v4
	v_mul_f32_e32 v5, 0x3fb8aa3b, v7
	v_exp_f32_e32 v5, v5
	v_pk_mul_f32 v[6:7], v[98:99], v[80:81]
	v_mul_f32_e32 v4, v5, v4
	v_cvt_pk_bf16_f32 v4, v4, s0
	ds_write_b16 v11, v4 offset:2448
	ds_read_u16 v4, v103 offset:58368
	v_add_f32_e32 v5, v109, v100
	s_waitcnt lgkmcnt(0)
	v_lshlrev_b32_e32 v88, 16, v4
	v_mul_f32_e32 v4, 0xbfb8aa3b, v5
	v_mul_f32_e32 v5, 0x3fb8aa3b, v5
	v_exp_f32_e32 v8, v5
	v_mul_f32_e32 v5, 0xbfb8aa3b, v9
	v_exp_f32_e32 v4, v4
	v_exp_f32_e32 v5, v5
	s_nop 0
	v_pk_mul_f32 v[4:5], v[6:7], v[4:5]
	s_nop 0
	v_cvt_pk_bf16_f32 v6, v4, s0
	ds_write_b16 v11, v6 offset:11424
	ds_read_u16 v6, v103 offset:50176
	v_cvt_pk_bf16_f32 v3, v4, v5
	s_waitcnt lgkmcnt(0)
	v_lshlrev_b32_e32 v6, 16, v6
	v_mul_f32_e32 v7, 0xbfb8aa3b, v6
	v_exp_f32_e32 v7, v7
	s_nop 0
	v_add_f32_e32 v7, 1.0, v7
	v_rcp_f32_e32 v7, v7
	s_nop 0
	v_mul_f32_e32 v6, v7, v6
	v_mul_f32_e32 v6, v8, v6
	v_cvt_pk_bf16_f32 v6, v6, s0
	ds_write_b16 v11, v6 offset:2720
	ds_read_u16 v6, v103 offset:58624
	s_waitcnt lgkmcnt(0)
	v_lshlrev_b32_e32 v80, 16, v6
	v_cvt_pk_bf16_f32 v6, v5, s0
	ds_write_b16 v11, v6 offset:11696
	ds_read_u16 v6, v103 offset:50432
	s_waitcnt lgkmcnt(0)
	v_lshlrev_b32_e32 v6, 16, v6
	v_mul_f32_e32 v7, 0xbfb8aa3b, v6
	v_exp_f32_e32 v7, v7
	s_nop 0
	v_add_f32_e32 v7, 1.0, v7
	v_rcp_f32_e32 v7, v7
	s_nop 0
	v_mul_f32_e32 v6, v7, v6
	v_mul_f32_e32 v7, 0x3fb8aa3b, v9
	v_exp_f32_e32 v7, v7
	v_pk_mul_f32 v[8:9], v[94:95], v[84:85]
	v_add_f32_e32 v94, v101, v100
	v_mul_f32_e32 v6, v7, v6
	v_cvt_pk_bf16_f32 v6, v6, s0
	ds_write_b16 v11, v6 offset:2992
	ds_read_u16 v6, v103 offset:58880
	v_add_f32_e32 v7, v106, v100
	s_waitcnt lgkmcnt(0)
	v_lshlrev_b32_e32 v81, 16, v6
	v_mul_f32_e32 v6, 0xbfb8aa3b, v7
	v_mul_f32_e32 v7, 0x3fb8aa3b, v7
	v_exp_f32_e32 v12, v7
	v_mul_f32_e32 v7, 0xbfb8aa3b, v13
	v_exp_f32_e32 v6, v6
	v_exp_f32_e32 v7, v7
	s_nop 0
	v_pk_mul_f32 v[6:7], v[8:9], v[6:7]
	s_nop 0
	v_cvt_pk_bf16_f32 v8, v6, s0
	ds_write_b16 v11, v8 offset:11968
	ds_read_u16 v8, v103 offset:50688
	v_cvt_pk_bf16_f32 v4, v6, v7
	s_waitcnt lgkmcnt(0)
	v_lshlrev_b32_e32 v8, 16, v8
	v_mul_f32_e32 v9, 0xbfb8aa3b, v8
	v_exp_f32_e32 v9, v9
	s_nop 0
	v_add_f32_e32 v9, 1.0, v9
	v_rcp_f32_e32 v9, v9
	s_nop 0
	v_mul_f32_e32 v8, v9, v8
	v_mul_f32_e32 v8, v12, v8
	v_cvt_pk_bf16_f32 v8, v8, s0
	ds_write_b16 v11, v8 offset:3264
	ds_read_u16 v8, v103 offset:59136
	s_waitcnt lgkmcnt(0)
	v_lshlrev_b32_e32 v84, 16, v8
	v_cvt_pk_bf16_f32 v8, v7, s0
	ds_write_b16 v11, v8 offset:12240
	ds_read_u16 v8, v103 offset:50944
	s_waitcnt lgkmcnt(0)
	v_lshlrev_b32_e32 v8, 16, v8
	v_mul_f32_e32 v9, 0xbfb8aa3b, v8
	v_exp_f32_e32 v9, v9
	s_nop 0
	v_add_f32_e32 v9, 1.0, v9
	v_rcp_f32_e32 v9, v9
	s_nop 0
	v_mul_f32_e32 v8, v9, v8
	v_mul_f32_e32 v9, 0x3fb8aa3b, v13
	v_exp_f32_e32 v9, v9
	v_pk_mul_f32 v[12:13], v[92:93], v[86:87]
	v_mul_f32_e32 v8, v9, v8
	v_cvt_pk_bf16_f32 v8, v8, s0
	ds_write_b16 v11, v8 offset:3536
	ds_read_u16 v8, v103 offset:59392
	v_add_f32_e32 v9, v102, v100
	s_waitcnt lgkmcnt(0)
	v_lshlrev_b32_e32 v85, 16, v8
	v_mul_f32_e32 v8, 0xbfb8aa3b, v9
	v_mul_f32_e32 v9, 0x3fb8aa3b, v9
	v_exp_f32_e32 v89, v9
	v_mul_f32_e32 v9, 0xbfb8aa3b, v94
	v_exp_f32_e32 v8, v8
	v_exp_f32_e32 v9, v9
	s_nop 0
	v_pk_mul_f32 v[8:9], v[12:13], v[8:9]
	s_nop 0
	v_cvt_pk_bf16_f32 v12, v8, s0
	ds_write_b16 v11, v12 offset:12512
	ds_read_u16 v12, v103 offset:51200
	v_cvt_pk_bf16_f32 v5, v8, v9
	s_waitcnt lgkmcnt(0)
	v_lshlrev_b32_e32 v12, 16, v12
	v_mul_f32_e32 v13, 0xbfb8aa3b, v12
	v_exp_f32_e32 v13, v13
	s_nop 0
	v_add_f32_e32 v13, 1.0, v13
	v_rcp_f32_e32 v13, v13
	s_nop 0
	v_mul_f32_e32 v12, v13, v12
	v_mul_f32_e32 v12, v89, v12
	v_cvt_pk_bf16_f32 v12, v12, s0
	v_mul_lo_u32 v13, v90, s1
	ds_write_b16 v11, v12 offset:3808
	v_cvt_pk_bf16_f32 v12, v9, s0
	v_add_lshl_u32 v0, v13, v0, 1
	ds_read_u16 v11, v91 offset:55808
	ds_write_b16 v0, v12 offset:8704
	ds_read_u16 v12, v91 offset:47616
	s_waitcnt lgkmcnt(2)
	v_lshlrev_b32_e32 v11, 16, v11
	s_waitcnt lgkmcnt(0)
	v_lshlrev_b32_e32 v12, 16, v12
	v_mul_f32_e32 v13, 0xbfb8aa3b, v12
	v_exp_f32_e32 v13, v13
	s_nop 0
	v_add_f32_e32 v13, 1.0, v13
	v_rcp_f32_e32 v13, v13
	s_nop 0
	v_mul_f32_e32 v12, v13, v12
	v_mul_f32_e32 v13, 0x3fb8aa3b, v94
	v_exp_f32_e32 v13, v13
	s_nop 0
	v_mul_f32_e32 v12, v13, v12
	v_cvt_pk_bf16_f32 v12, v12, s0
	ds_write_b16 v0, v12
	ds_write_b128 v10, v[2:5] offset:17424
	v_cvt_pk_bf16_f32 v2, v82, v83
	v_cvt_pk_bf16_f32 v3, v88, v80
	v_cvt_pk_bf16_f32 v4, v81, v84
	v_cvt_pk_bf16_f32 v5, v85, v11
	ds_write_b128 v10, v[2:5] offset:27664
	s_waitcnt lgkmcnt(0)
	s_barrier
	s_nop 0
	v_and_b32_e32 v0, 31, v112
	v_bfe_u32 v113, v112, 5, 1
	s_setprio 1
	v_mul_u32_u24_e32 v2, 0x88, v0
	v_lshlrev_b32_e32 v3, 4, v113
	v_lshl_add_u32 v115, v2, 1, v3
	ds_read_b128 v[128:131], v115 offset:8704
	ds_read_b128 v[132:135], v115
	ds_read_b128 v[136:139], v115 offset:32
	ds_read_b128 v[140:143], v115 offset:8736
	ds_read_b128 v[144:147], v115 offset:8768
	ds_read_b128 v[148:151], v115 offset:64
	ds_read_b128 v[152:155], v115 offset:8800
	ds_read_b128 v[156:159], v115 offset:96
	ds_read_b128 v[160:163], v115 offset:8832
	ds_read_b128 v[164:167], v115 offset:128
	ds_read_b128 v[168:171], v115 offset:8864
	ds_read_b128 v[172:175], v115 offset:160
	v_lshlrev_b32_e32 v114, 3, v113
	v_lshlrev_b32_e32 v113, 2, v113
	s_waitcnt lgkmcnt(10)
	v_mfma_f32_32x32x16_bf16 v[80:95], v[128:131], v[132:135], 0
	ds_read_b128 v[128:131], v115 offset:8896
	ds_read_b128 v[132:135], v115 offset:192
	v_cmp_le_u32_e32 vcc, v113, v0
	v_or_b32_e32 v116, 3, v113
	v_or_b32_e32 v117, 2, v113
	s_waitcnt lgkmcnt(10)
	v_mfma_f32_32x32x16_bf16 v[96:111], v[140:143], v[136:139], 0
	ds_read_b128 v[140:143], v115 offset:8928
	ds_read_b128 v[136:139], v115 offset:224
	s_waitcnt lgkmcnt(10)
	v_mfma_f32_32x32x16_bf16 v[80:95], v[144:147], v[148:151], v[80:95]
	s_waitcnt lgkmcnt(8)
	v_mfma_f32_32x32x16_bf16 v[96:111], v[152:155], v[156:159], v[96:111]
	s_waitcnt lgkmcnt(6)
	v_mfma_f32_32x32x16_bf16 v[80:95], v[160:163], v[164:167], v[80:95]
	s_waitcnt lgkmcnt(4)
	v_mfma_f32_32x32x16_bf16 v[96:111], v[168:171], v[172:175], v[96:111]
	s_waitcnt lgkmcnt(2)
	v_mfma_f32_32x32x16_bf16 v[80:95], v[128:131], v[132:135], v[80:95]
	s_waitcnt lgkmcnt(0)
	v_mfma_f32_32x32x16_bf16 v[96:111], v[140:143], v[136:139], v[96:111]
	s_nop 11
	v_add_f32_e32 v2, v80, v96
	v_cndmask_b32_e32 v96, 0, v2, vcc
	v_cmp_lt_u32_e32 vcc, v113, v0
	v_add_f32_e32 v2, v81, v97
	v_pk_add_f32 v[10:11], v[86:87], v[102:103]
	v_cndmask_b32_e32 v97, 0, v2, vcc
	v_pk_add_f32 v[8:9], v[84:85], v[100:101]
	v_pk_add_f32 v[12:13], v[82:83], v[98:99]
	v_pk_add_f32 v[80:81], v[94:95], v[110:111]
	v_pk_add_f32 v[4:5], v[92:93], v[108:109]
	v_pk_add_f32 v[6:7], v[90:91], v[106:107]
	v_pk_add_f32 v[2:3], v[88:89], v[104:105]
	v_or_b32_e32 v82, 9, v113
	v_or_b32_e32 v83, 8, v113
	v_or_b32_e32 v84, 11, v113
	v_or_b32_e32 v85, 10, v113
	v_or_b32_e32 v86, 17, v113
	v_or_b32_e32 v87, 16, v113
	v_or_b32_e32 v88, 19, v113
	v_or_b32_e32 v89, 18, v113
	v_or_b32_e32 v90, 25, v113
	v_or_b32_e32 v91, 24, v113
	v_or_b32_e32 v98, 27, v113
	v_or_b32_e32 v92, 26, v113
	v_cvt_pk_bf16_f32 v2, v2, v3
	v_cmp_le_u32_e32 vcc, v87, v0
	v_cvt_pk_bf16_f32 v4, v4, v5
	v_ashrrev_i32_e32 v99, 1, v112
	v_cndmask_b32_e32 v3, 0, v2, vcc
	v_lshrrev_b32_e32 v2, 16, v2
	v_cmp_le_u32_e32 vcc, v86, v0
	s_movk_i32 s1, 0xffe0
	v_bfi_b32 v93, s1, v99, v112
	v_cndmask_b32_e32 v2, 0, v2, vcc
	v_perm_b32 v2, v2, v3, s78
	v_cvt_pk_bf16_f32 v3, v6, v7
	v_cmp_le_u32_e32 vcc, v89, v0
	v_mul_lo_u32 v93, v93, s87
	v_or_b32_e32 v93, v93, v114
	v_cndmask_b32_e32 v6, 0, v3, vcc
	v_lshrrev_b32_e32 v3, 16, v3
	v_cmp_le_u32_e32 vcc, v88, v0
	s_nop 1
	v_cndmask_b32_e32 v3, 0, v3, vcc
	v_cmp_le_u32_e32 vcc, v91, v0
	v_perm_b32 v3, v3, v6, s78
	v_cvt_pk_bf16_f32 v6, v96, v97
	v_cndmask_b32_e32 v5, 0, v4, vcc
	v_lshrrev_b32_e32 v4, 16, v4
	v_cmp_le_u32_e32 vcc, v90, v0
	v_add_u32_e32 v96, 0x6800, v93
	s_nop 0
	v_cndmask_b32_e32 v4, 0, v4, vcc
	v_perm_b32 v4, v4, v5, s78
	v_cvt_pk_bf16_f32 v5, v12, v13
	v_cmp_le_u32_e32 vcc, v117, v0
	s_nop 1
	v_cndmask_b32_e32 v7, 0, v5, vcc
	v_lshrrev_b32_e32 v5, 16, v5
	v_cmp_le_u32_e32 vcc, v116, v0
	s_nop 1
	v_cndmask_b32_e32 v5, 0, v5, vcc
	v_perm_b32 v7, v5, v7, s78
	v_cvt_pk_bf16_f32 v5, v8, v9
	v_cmp_le_u32_e32 vcc, v83, v0
	s_nop 1
	v_cndmask_b32_e32 v8, 0, v5, vcc
	v_lshrrev_b32_e32 v5, 16, v5
	v_cmp_le_u32_e32 vcc, v82, v0
	s_nop 1
	v_cndmask_b32_e32 v5, 0, v5, vcc
	v_perm_b32 v8, v5, v8, s78
	v_cvt_pk_bf16_f32 v5, v10, v11
	v_cmp_le_u32_e32 vcc, v85, v0
	ds_read2_b64 v[10:13], v96 offset0:128 offset1:130
	s_nop 0
	v_cndmask_b32_e32 v9, 0, v5, vcc
	v_lshrrev_b32_e32 v5, 16, v5
	v_cmp_le_u32_e32 vcc, v84, v0
	s_nop 1
	v_cndmask_b32_e32 v5, 0, v5, vcc
	v_perm_b32 v9, v5, v9, s78
	v_cvt_pk_bf16_f32 v5, v80, v81
	v_cmp_le_u32_e32 vcc, v92, v0
	s_waitcnt lgkmcnt(0)
	v_mfma_f32_32x32x16_bf16 v[80:95], v[6:9], v[10:13], 0
	v_cndmask_b32_e32 v97, 0, v5, vcc
	v_lshrrev_b32_e32 v5, 16, v5
	v_cmp_le_u32_e32 vcc, v98, v0
	ds_read2_b64 v[6:9], v96 offset0:132 offset1:134
	v_and_b32_e32 v10, 0xffffffe0, v99
	v_cndmask_b32_e32 v5, 0, v5, vcc
	v_perm_b32 v5, v5, v97, s78
	s_waitcnt lgkmcnt(0)
	s_nop 0
	v_mfma_f32_32x32x16_bf16 v[80:95], v[2:5], v[6:9], v[80:95]
	v_sub_u32_e32 v11, v115, v114
	ds_read2_b64 v[2:5], v11 offset1:2
	v_cvt_pk_bf16_f32 v6, v16, v17
	v_cvt_pk_bf16_f32 v7, v18, v19
	v_cvt_pk_bf16_f32 v8, v20, v21
	v_cvt_pk_bf16_f32 v9, v22, v23
	s_waitcnt lgkmcnt(0)
	s_nop 0
	v_mfma_f32_32x32x16_bf16 v[80:95], v[2:5], v[6:9], v[80:95]
	ds_read2_b64 v[2:5], v11 offset0:4 offset1:6
	v_cvt_pk_bf16_f32 v6, v24, v25
	v_cvt_pk_bf16_f32 v7, v26, v27
	v_cvt_pk_bf16_f32 v8, v28, v29
	v_cvt_pk_bf16_f32 v9, v30, v31
	s_waitcnt lgkmcnt(0)
	s_nop 0
	v_mfma_f32_32x32x16_bf16 v[96:111], v[2:5], v[6:9], 0
	ds_read2_b64 v[2:5], v11 offset0:8 offset1:10
	v_cvt_pk_bf16_f32 v6, v32, v33
	v_cvt_pk_bf16_f32 v7, v34, v35
	v_cvt_pk_bf16_f32 v8, v36, v37
	v_cvt_pk_bf16_f32 v9, v38, v39
	s_waitcnt lgkmcnt(0)
	s_nop 0
	v_mfma_f32_32x32x16_bf16 v[80:95], v[2:5], v[6:9], v[80:95]
	ds_read2_b64 v[2:5], v11 offset0:12 offset1:14
	v_cvt_pk_bf16_f32 v6, v40, v41
	v_cvt_pk_bf16_f32 v7, v42, v43
	v_cvt_pk_bf16_f32 v8, v44, v45
	v_cvt_pk_bf16_f32 v9, v46, v47
	s_waitcnt lgkmcnt(0)
	s_nop 0
	v_mfma_f32_32x32x16_bf16 v[96:111], v[2:5], v[6:9], v[96:111]
	ds_read2_b64 v[2:5], v11 offset0:16 offset1:18
	v_cvt_pk_bf16_f32 v6, v48, v49
	v_cvt_pk_bf16_f32 v7, v50, v51
	v_cvt_pk_bf16_f32 v8, v52, v53
	v_cvt_pk_bf16_f32 v9, v54, v55
	s_waitcnt lgkmcnt(0)
	s_nop 0
	v_mfma_f32_32x32x16_bf16 v[80:95], v[2:5], v[6:9], v[80:95]
	ds_read2_b64 v[2:5], v11 offset0:20 offset1:22
	v_cvt_pk_bf16_f32 v6, v56, v57
	v_cvt_pk_bf16_f32 v7, v58, v59
	v_cvt_pk_bf16_f32 v8, v60, v61
	v_cvt_pk_bf16_f32 v9, v62, v63
	s_waitcnt lgkmcnt(0)
	s_nop 0
	v_mfma_f32_32x32x16_bf16 v[96:111], v[2:5], v[6:9], v[96:111]
	ds_read2_b64 v[2:5], v11 offset0:24 offset1:26
	v_cvt_pk_bf16_f32 v6, v64, v65
	v_cvt_pk_bf16_f32 v7, v66, v67
	v_cvt_pk_bf16_f32 v8, v68, v69
	v_cvt_pk_bf16_f32 v9, v70, v71
	s_waitcnt lgkmcnt(0)
	s_nop 0
	v_mfma_f32_32x32x16_bf16 v[80:95], v[2:5], v[6:9], v[80:95]
	ds_read2_b64 v[2:5], v11 offset0:28 offset1:30
	v_cvt_pk_bf16_f32 v6, v72, v73
	v_cvt_pk_bf16_f32 v7, v74, v75
	v_cvt_pk_bf16_f32 v8, v76, v77
	v_cvt_pk_bf16_f32 v9, v78, v79
	s_waitcnt lgkmcnt(0)
	s_nop 0
	v_mfma_f32_32x32x16_bf16 v[96:111], v[2:5], v[6:9], v[96:111]
	s_nop 11
	v_add_f32_e32 v8, v80, v96
	v_add_f32_e32 v9, v81, v97
	v_add_f32_e32 v12, v82, v98
	v_add_f32_e32 v13, v83, v99
	v_add_f32_e32 v80, v84, v100
	v_add_f32_e32 v81, v85, v101
	v_add_f32_e32 v82, v86, v102
	v_add_f32_e32 v83, v87, v103
	v_add_f32_e32 v84, v88, v104
	v_add_f32_e32 v85, v89, v105
	v_add_f32_e32 v86, v90, v106
	v_add_f32_e32 v87, v91, v107
	v_add_f32_e32 v88, v92, v108
	v_add_f32_e32 v89, v93, v109
	v_add_f32_e32 v90, v94, v110
	v_add_f32_e32 v91, v95, v111
	v_add_u32_e32 v2, s27, v113
	v_ashrrev_i32_e32 v11, 31, v10
	v_lshl_add_u64 v[4:5], v[10:11], 2, s[36:37]
	v_lshlrev_b32_e32 v0, 2, v0
	v_ashrrev_i32_e32 v3, 31, v2
	v_lshl_add_u64 v[4:5], v[4:5], 0, v[0:1]
	v_lshlrev_b64 v[6:7], 11, v[2:3]
	v_lshl_add_u64 v[6:7], v[4:5], 0, v[6:7]
	global_store_dword v[6:7], v8, off
	v_add_u32_e32 v6, 1, v2
	v_ashrrev_i32_e32 v7, 31, v6
	v_lshlrev_b64 v[6:7], 11, v[6:7]
	v_lshl_add_u64 v[6:7], v[4:5], 0, v[6:7]
	global_store_dword v[6:7], v9, off
	v_add_u32_e32 v6, 2, v2
	v_ashrrev_i32_e32 v7, 31, v6
	v_lshlrev_b64 v[6:7], 11, v[6:7]
	v_lshl_add_u64 v[6:7], v[4:5], 0, v[6:7]
	global_store_dword v[6:7], v12, off
	v_add_u32_e32 v6, 3, v2
	v_ashrrev_i32_e32 v7, 31, v6
	v_lshlrev_b64 v[6:7], 11, v[6:7]
	v_lshl_add_u64 v[6:7], v[4:5], 0, v[6:7]
	global_store_dword v[6:7], v13, off
	v_add_u32_e32 v6, 8, v2
	v_ashrrev_i32_e32 v7, 31, v6
	v_lshlrev_b64 v[6:7], 11, v[6:7]
	v_lshl_add_u64 v[6:7], v[4:5], 0, v[6:7]
	global_store_dword v[6:7], v80, off
	v_add_u32_e32 v6, 9, v2
	v_ashrrev_i32_e32 v7, 31, v6
	v_lshlrev_b64 v[6:7], 11, v[6:7]
	v_lshl_add_u64 v[6:7], v[4:5], 0, v[6:7]
	global_store_dword v[6:7], v81, off
	v_add_u32_e32 v6, 10, v2
	v_ashrrev_i32_e32 v7, 31, v6
	v_lshlrev_b64 v[6:7], 11, v[6:7]
	v_lshl_add_u64 v[6:7], v[4:5], 0, v[6:7]
	global_store_dword v[6:7], v82, off
	v_add_u32_e32 v6, 11, v2
	v_ashrrev_i32_e32 v7, 31, v6
	v_lshlrev_b64 v[6:7], 11, v[6:7]
	v_lshl_add_u64 v[6:7], v[4:5], 0, v[6:7]
	global_store_dword v[6:7], v83, off
	v_add_u32_e32 v6, 16, v2
	v_ashrrev_i32_e32 v7, 31, v6
	v_lshlrev_b64 v[6:7], 11, v[6:7]
	v_lshl_add_u64 v[6:7], v[4:5], 0, v[6:7]
	global_store_dword v[6:7], v84, off
	v_add_u32_e32 v6, 17, v2
	v_ashrrev_i32_e32 v7, 31, v6
	v_lshlrev_b64 v[6:7], 11, v[6:7]
	v_lshl_add_u64 v[6:7], v[4:5], 0, v[6:7]
	global_store_dword v[6:7], v85, off
	v_add_u32_e32 v6, 18, v2
	v_ashrrev_i32_e32 v7, 31, v6
	v_lshlrev_b64 v[6:7], 11, v[6:7]
	v_lshl_add_u64 v[6:7], v[4:5], 0, v[6:7]
	global_store_dword v[6:7], v86, off
	v_add_u32_e32 v6, 19, v2
	v_ashrrev_i32_e32 v7, 31, v6
	v_lshlrev_b64 v[6:7], 11, v[6:7]
	v_lshl_add_u64 v[6:7], v[4:5], 0, v[6:7]
	global_store_dword v[6:7], v87, off
	v_add_u32_e32 v6, 24, v2
	v_ashrrev_i32_e32 v7, 31, v6
	v_lshlrev_b64 v[6:7], 11, v[6:7]
	v_lshl_add_u64 v[6:7], v[4:5], 0, v[6:7]
	global_store_dword v[6:7], v88, off
	v_add_u32_e32 v6, 25, v2
	v_ashrrev_i32_e32 v7, 31, v6
	v_lshlrev_b64 v[6:7], 11, v[6:7]
	v_lshl_add_u64 v[6:7], v[4:5], 0, v[6:7]
	global_store_dword v[6:7], v89, off
	v_add_u32_e32 v6, 26, v2
	v_add_u32_e32 v2, 27, v2
	v_ashrrev_i32_e32 v7, 31, v6
	v_ashrrev_i32_e32 v3, 31, v2
	v_lshlrev_b64 v[6:7], 11, v[6:7]
	v_lshlrev_b64 v[2:3], 11, v[2:3]
	v_lshl_add_u64 v[6:7], v[4:5], 0, v[6:7]
	v_lshl_add_u64 v[2:3], v[4:5], 0, v[2:3]
	global_store_dword v[6:7], v90, off
	global_store_dword v[2:3], v91, off
	s_setprio 1
	s_mov_b32 s1, 0xfffffe0
	v_and_b32_e32 v4, 31, v112
	v_lshrrev_b32_e32 v2, 1, v112
	v_and_b32_e32 v0, 16, v2
	v_and_or_b32 v2, v2, s1, v4
	v_mad_u64_u32 v[2:3], s[20:21], v2, s87, v[0:1]
	v_mad_u32_u24 v92, v4, s87, v0
	ds_read_b128 v[10:13], v92 offset:17408
	ds_read_b128 v[80:83], v92 offset:17440
	ds_read_b128 v[6:9], v2 offset:27648
	ds_read_b128 v[2:5], v2 offset:27680
	s_waitcnt lgkmcnt(1)
	v_mfma_f32_32x32x16_bf16 v[16:31], v[10:13], v[6:9], v[16:31]
	s_waitcnt lgkmcnt(0)
	v_mfma_f32_32x32x16_bf16 v[16:31], v[80:83], v[2:5], v[16:31]
	ds_read_b128 v[10:13], v0 offset:37888
	ds_read_b128 v[80:83], v0 offset:37920
	ds_read_b128 v[84:87], v0 offset:37952
	ds_read_b128 v[88:91], v0 offset:37984
	s_waitcnt lgkmcnt(3)
	s_nop 6
	v_pk_mul_f32 v[18:19], v[18:19], v[12:13]
	v_pk_mul_f32 v[16:17], v[16:17], v[10:11]
	ds_read_b128 v[10:13], v92 offset:19968
	s_waitcnt lgkmcnt(0)
	v_mfma_f32_32x32x16_bf16 v[32:47], v[10:13], v[6:9], v[32:47]
	ds_read_b128 v[10:13], v92 offset:20000
	v_mul_f32_e64 v30, v30, v90
	v_mul_f32_e64 v31, v31, v91
	v_mul_f32_e64 v28, v28, v88
	v_mul_f32_e64 v29, v29, v89
	v_pk_mul_f32 v[26:27], v[26:27], v[86:87]
	v_pk_mul_f32 v[24:25], v[24:25], v[84:85]
	v_pk_mul_f32 v[22:23], v[22:23], v[82:83]
	v_pk_mul_f32 v[20:21], v[20:21], v[80:81]
	s_waitcnt lgkmcnt(0)
	v_mfma_f32_32x32x16_bf16 v[32:47], v[10:13], v[2:5], v[32:47]
	ds_read_b128 v[10:13], v0 offset:38016
	ds_read_b128 v[80:83], v0 offset:38048
	ds_read_b128 v[84:87], v0 offset:38080
	ds_read_b128 v[88:91], v0 offset:38112
	s_waitcnt lgkmcnt(3)
	s_nop 6
	v_pk_mul_f32 v[34:35], v[34:35], v[12:13]
	v_pk_mul_f32 v[32:33], v[32:33], v[10:11]
	ds_read_b128 v[10:13], v92 offset:22528
	s_waitcnt lgkmcnt(0)
	v_mfma_f32_32x32x16_bf16 v[48:63], v[10:13], v[6:9], v[48:63]
	ds_read_b128 v[10:13], v92 offset:22560
	v_mul_f32_e64 v46, v46, v90
	v_mul_f32_e64 v47, v47, v91
	v_mul_f32_e64 v44, v44, v88
	v_mul_f32_e64 v45, v45, v89
	v_pk_mul_f32 v[42:43], v[42:43], v[86:87]
	v_pk_mul_f32 v[40:41], v[40:41], v[84:85]
	v_pk_mul_f32 v[38:39], v[38:39], v[82:83]
	v_pk_mul_f32 v[36:37], v[36:37], v[80:81]
	s_waitcnt lgkmcnt(0)
	v_mfma_f32_32x32x16_bf16 v[48:63], v[10:13], v[2:5], v[48:63]
	ds_read_b128 v[10:13], v0 offset:38144
	ds_read_b128 v[80:83], v0 offset:38176
	ds_read_b128 v[84:87], v0 offset:38208
	ds_read_b128 v[88:91], v0 offset:38240
	s_waitcnt lgkmcnt(3)
	s_nop 6
	v_pk_mul_f32 v[50:51], v[50:51], v[12:13]
	v_pk_mul_f32 v[48:49], v[48:49], v[10:11]
	ds_read_b128 v[10:13], v92 offset:25088
	s_waitcnt lgkmcnt(0)
	v_mfma_f32_32x32x16_bf16 v[64:79], v[10:13], v[6:9], v[64:79]
	ds_read_b128 v[6:9], v92 offset:25120
	v_mul_f32_e64 v54, v54, v82
	v_mul_f32_e64 v55, v55, v83
	v_mul_f32_e64 v52, v52, v80
	v_mul_f32_e64 v53, v53, v81
	v_pk_mul_f32 v[62:63], v[62:63], v[90:91]
	v_pk_mul_f32 v[60:61], v[60:61], v[88:89]
	v_pk_mul_f32 v[58:59], v[58:59], v[86:87]
	v_pk_mul_f32 v[56:57], v[56:57], v[84:85]
	s_waitcnt lgkmcnt(0)
	v_mfma_f32_32x32x16_bf16 v[64:79], v[6:9], v[2:5], v[64:79]
	ds_read_b128 v[2:5], v0 offset:38272
	ds_read_b128 v[6:9], v0 offset:38304
	ds_read_b128 v[10:13], v0 offset:38336
	ds_read_b128 v[80:83], v0 offset:38368
	s_waitcnt lgkmcnt(0)
	s_nop 6
	v_pk_mul_f32 v[78:79], v[78:79], v[82:83]
	v_pk_mul_f32 v[76:77], v[76:77], v[80:81]
	v_pk_mul_f32 v[74:75], v[74:75], v[12:13]
	v_pk_mul_f32 v[72:73], v[72:73], v[10:11]
	v_pk_mul_f32 v[70:71], v[70:71], v[8:9]
	v_pk_mul_f32 v[68:69], v[68:69], v[6:7]
	v_pk_mul_f32 v[66:67], v[66:67], v[4:5]
	v_pk_mul_f32 v[64:65], v[64:65], v[2:3]
	s_setprio 0
	s_add_i32 s26, s26, 32
	s_cmpk_eq_i32 s26, 0x100
	s_cbranch_scc1 .LBB0_305
